# out-proj epilogue: bf16 tile permuted across lanes (ds_bpermute) so each lane quad writes one contiguous 64-byte row segment
# speedup vs baseline: 1.0042x; 1.0001x over previous
.LBB0_50:
	v_mov_b32_e32 v128, v250
	v_bfe_u32 v216, v250, 2, 4
	v_and_b32_e32 v217, 3, v250
	v_lshl_or_b32 v216, v217, 4, v216
	v_lshlrev_b32_e32 v216, 2, v216
	v_cvt_pk_bf16_f32 v104, v104, v105
	v_readfirstlane_b32 s2, v128
	s_ashr_i32 s3, s2, 2
	s_lshr_b32 s2, s2, 1
	s_and_b32 s2, s2, 0x60
	v_and_b32_e32 v129, 3, v128
	s_andn2_b32 s3, s3, 63
	v_lshl_or_b32 v129, v129, 3, s2
	v_bfe_u32 v128, v128, 2, 4
	v_or_b32_e32 v128, s6, v128
	v_or_b32_e32 v129, s36, v129
	v_add_u32_e32 v128, s3, v128
	v_lshlrev_b32_e32 v176, 1, v129
	v_ashrrev_i32_e32 v129, 31, v128
	v_lshl_add_u64 v[130:131], s[70:71], 0, v[176:177]
	v_lshlrev_b64 v[132:133], 11, v[128:129]
	v_lshl_add_u64 v[132:133], v[130:131], 0, v[132:133]
	v_cvt_pk_bf16_f32 v105, v106, v107
	v_cvt_pk_bf16_f32 v106, v108, v109
	v_cvt_pk_bf16_f32 v107, v110, v111
	v_mov_b64_e32 v[218:219], v[132:133]
	ds_bpermute_b32 v208, v216, v104
	ds_bpermute_b32 v209, v216, v105
	ds_bpermute_b32 v210, v216, v106
	ds_bpermute_b32 v211, v216, v107
	v_cvt_pk_bf16_f32 v80, v80, v81
	v_cvt_pk_bf16_f32 v81, v82, v83
	v_cvt_pk_bf16_f32 v104, v120, v121
	v_cvt_pk_bf16_f32 v105, v122, v123
	v_cvt_pk_bf16_f32 v106, v124, v125
	v_cvt_pk_bf16_f32 v107, v126, v127
	v_mov_b64_e32 v[220:221], v[132:133]
	ds_bpermute_b32 v212, v216, v104
	ds_bpermute_b32 v213, v216, v105
	ds_bpermute_b32 v214, v216, v106
	ds_bpermute_b32 v215, v216, v107
	s_waitcnt lgkmcnt(4)
	global_store_dwordx4 v[218:219], v[208:211], off
	v_cvt_pk_bf16_f32 v82, v84, v85
	v_cvt_pk_bf16_f32 v83, v86, v87
	v_or_b32_e32 v104, 16, v128
	v_ashrrev_i32_e32 v105, 31, v104
	v_lshlrev_b64 v[104:105], 11, v[104:105]
	v_lshl_add_u64 v[104:105], v[130:131], 0, v[104:105]
	v_mov_b64_e32 v[218:219], v[104:105]
	ds_bpermute_b32 v208, v216, v80
	ds_bpermute_b32 v209, v216, v81
	ds_bpermute_b32 v210, v216, v82
	ds_bpermute_b32 v211, v216, v83
	s_waitcnt lgkmcnt(4)
	global_store_dwordx4 v[220:221], v[212:215], off offset:256
	v_cvt_pk_bf16_f32 v48, v48, v49
	v_cvt_pk_bf16_f32 v49, v50, v51
	v_cvt_pk_bf16_f32 v80, v112, v113
	v_cvt_pk_bf16_f32 v81, v114, v115
	v_cvt_pk_bf16_f32 v82, v116, v117
	v_cvt_pk_bf16_f32 v83, v118, v119
	v_mov_b64_e32 v[220:221], v[104:105]
	ds_bpermute_b32 v212, v216, v80
	ds_bpermute_b32 v213, v216, v81
	ds_bpermute_b32 v214, v216, v82
	ds_bpermute_b32 v215, v216, v83
	s_waitcnt lgkmcnt(4)
	global_store_dwordx4 v[218:219], v[208:211], off
	v_cvt_pk_bf16_f32 v50, v52, v53
	v_cvt_pk_bf16_f32 v51, v54, v55
	v_or_b32_e32 v80, 32, v128
	v_ashrrev_i32_e32 v81, 31, v80
	v_lshlrev_b64 v[80:81], 11, v[80:81]
	v_lshl_add_u64 v[80:81], v[130:131], 0, v[80:81]
	v_mov_b64_e32 v[218:219], v[80:81]
	ds_bpermute_b32 v208, v216, v48
	ds_bpermute_b32 v209, v216, v49
	ds_bpermute_b32 v210, v216, v50
	ds_bpermute_b32 v211, v216, v51
	s_waitcnt lgkmcnt(4)
	global_store_dwordx4 v[220:221], v[212:215], off offset:256
	s_mov_b64 s[2:3], 0x40000
	v_cvt_pk_bf16_f32 v32, v32, v33
	v_cvt_pk_bf16_f32 v48, v96, v97
	v_cvt_pk_bf16_f32 v49, v98, v99
	v_cvt_pk_bf16_f32 v50, v100, v101
	v_cvt_pk_bf16_f32 v51, v102, v103
	v_mov_b64_e32 v[220:221], v[80:81]
	ds_bpermute_b32 v212, v216, v48
	ds_bpermute_b32 v213, v216, v49
	ds_bpermute_b32 v214, v216, v50
	ds_bpermute_b32 v215, v216, v51
	s_waitcnt lgkmcnt(4)
	global_store_dwordx4 v[218:219], v[208:211], off
	v_cvt_pk_bf16_f32 v33, v34, v35
	v_cvt_pk_bf16_f32 v34, v36, v37
	v_or_b32_e32 v48, 48, v128
	v_ashrrev_i32_e32 v49, 31, v48
	v_lshlrev_b64 v[48:49], 11, v[48:49]
	v_lshl_add_u64 v[48:49], v[130:131], 0, v[48:49]
	v_cvt_pk_bf16_f32 v35, v38, v39
	v_lshl_add_u64 v[36:37], v[132:133], 0, s[2:3]
	s_mov_b32 s2, 0x40000
	v_mov_b64_e32 v[218:219], v[48:49]
	ds_bpermute_b32 v208, v216, v32
	ds_bpermute_b32 v209, v216, v33
	ds_bpermute_b32 v210, v216, v34
	ds_bpermute_b32 v211, v216, v35
	s_waitcnt lgkmcnt(4)
	global_store_dwordx4 v[220:221], v[212:215], off offset:256
	v_add_co_u32_e32 v38, vcc, s2, v132
	s_nop 0
	v_cvt_pk_bf16_f32 v32, v64, v65
	v_cvt_pk_bf16_f32 v33, v66, v67
	v_cvt_pk_bf16_f32 v34, v68, v69
	v_cvt_pk_bf16_f32 v35, v70, v71
	v_mov_b64_e32 v[220:221], v[48:49]
	ds_bpermute_b32 v212, v216, v32
	ds_bpermute_b32 v213, v216, v33
	ds_bpermute_b32 v214, v216, v34
	ds_bpermute_b32 v215, v216, v35
	s_waitcnt lgkmcnt(4)
	global_store_dwordx4 v[218:219], v[208:211], off
	v_addc_co_u32_e32 v39, vcc, 0, v133, vcc
	s_nop 0
	v_cvt_pk_bf16_f32 v32, v72, v73
	v_cvt_pk_bf16_f32 v33, v74, v75
	v_cvt_pk_bf16_f32 v34, v76, v77
	v_cvt_pk_bf16_f32 v35, v78, v79
	v_mov_b64_e32 v[218:219], v[38:39]
	ds_bpermute_b32 v208, v216, v32
	ds_bpermute_b32 v209, v216, v33
	ds_bpermute_b32 v210, v216, v34
	ds_bpermute_b32 v211, v216, v35
	s_waitcnt lgkmcnt(4)
	global_store_dwordx4 v[220:221], v[212:215], off offset:256
	s_mov_b64 s[2:3], 0x48000
	v_cvt_pk_bf16_f32 v16, v16, v17
	v_cvt_pk_bf16_f32 v32, v88, v89
	v_cvt_pk_bf16_f32 v33, v90, v91
	v_cvt_pk_bf16_f32 v34, v92, v93
	v_cvt_pk_bf16_f32 v35, v94, v95
	v_mov_b64_e32 v[220:221], v[36:37]
	ds_bpermute_b32 v212, v216, v32
	ds_bpermute_b32 v213, v216, v33
	ds_bpermute_b32 v214, v216, v34
	ds_bpermute_b32 v215, v216, v35
	s_waitcnt lgkmcnt(4)
	global_store_dwordx4 v[218:219], v[208:211], off
	v_lshl_add_u64 v[36:37], v[132:133], 0, s[2:3]
	s_mov_b32 s2, 0x48000
	v_add_co_u32_e32 v38, vcc, s2, v132
	v_cvt_pk_bf16_f32 v32, v40, v41
	v_cvt_pk_bf16_f32 v33, v42, v43
	v_cvt_pk_bf16_f32 v34, v44, v45
	v_cvt_pk_bf16_f32 v35, v46, v47
	v_addc_co_u32_e32 v39, vcc, 0, v133, vcc
	v_mov_b64_e32 v[218:219], v[38:39]
	ds_bpermute_b32 v208, v216, v32
	ds_bpermute_b32 v209, v216, v33
	ds_bpermute_b32 v210, v216, v34
	ds_bpermute_b32 v211, v216, v35
	s_waitcnt lgkmcnt(4)
	global_store_dwordx4 v[220:221], v[212:215], off offset:256
	s_mov_b64 s[2:3], 0x50000
	v_cvt_pk_bf16_f32 v17, v18, v19
	v_cvt_pk_bf16_f32 v32, v56, v57
	v_cvt_pk_bf16_f32 v33, v58, v59
	v_cvt_pk_bf16_f32 v34, v60, v61
	v_cvt_pk_bf16_f32 v35, v62, v63
	v_mov_b64_e32 v[220:221], v[36:37]
	ds_bpermute_b32 v212, v216, v32
	ds_bpermute_b32 v213, v216, v33
	ds_bpermute_b32 v214, v216, v34
	ds_bpermute_b32 v215, v216, v35
	s_waitcnt lgkmcnt(4)
	global_store_dwordx4 v[218:219], v[208:211], off
	v_cvt_pk_bf16_f32 v18, v20, v21
	v_cvt_pk_bf16_f32 v19, v22, v23
	v_lshl_add_u64 v[32:33], v[132:133], 0, s[2:3]
	s_mov_b32 s2, 0x50000
	v_add_co_u32_e32 v20, vcc, s2, v132
	s_mov_b64 s[2:3], 0x58000
	s_nop 0
	v_addc_co_u32_e32 v21, vcc, 0, v133, vcc
	v_mov_b64_e32 v[218:219], v[20:21]
	ds_bpermute_b32 v208, v216, v16
	ds_bpermute_b32 v209, v216, v17
	ds_bpermute_b32 v210, v216, v18
	ds_bpermute_b32 v211, v216, v19
	s_waitcnt lgkmcnt(4)
	global_store_dwordx4 v[220:221], v[212:215], off offset:256
	v_cvt_pk_bf16_f32 v0, v0, v1
	v_cvt_pk_bf16_f32 v1, v2, v3
	v_cvt_pk_bf16_f32 v16, v24, v25
	v_cvt_pk_bf16_f32 v17, v26, v27
	v_cvt_pk_bf16_f32 v18, v28, v29
	v_cvt_pk_bf16_f32 v19, v30, v31
	v_mov_b64_e32 v[220:221], v[32:33]
	ds_bpermute_b32 v212, v216, v16
	ds_bpermute_b32 v213, v216, v17
	ds_bpermute_b32 v214, v216, v18
	ds_bpermute_b32 v215, v216, v19
	s_waitcnt lgkmcnt(4)
	global_store_dwordx4 v[218:219], v[208:211], off
	v_cvt_pk_bf16_f32 v2, v4, v5
	v_cvt_pk_bf16_f32 v3, v6, v7
	v_lshl_add_u64 v[16:17], v[132:133], 0, s[2:3]
	s_mov_b32 s2, 0x58000
	v_add_co_u32_e32 v4, vcc, s2, v132
	s_mov_b64 s[2:3], -1
	s_nop 0
	v_addc_co_u32_e32 v5, vcc, 0, v133, vcc
	v_mov_b64_e32 v[218:219], v[4:5]
	ds_bpermute_b32 v208, v216, v0
	ds_bpermute_b32 v209, v216, v1
	ds_bpermute_b32 v210, v216, v2
	ds_bpermute_b32 v211, v216, v3
	s_waitcnt lgkmcnt(4)
	global_store_dwordx4 v[220:221], v[212:215], off offset:256
	s_and_b64 vcc, exec, s[0:1]
	s_mov_b32 s7, s35
	v_cvt_pk_bf16_f32 v0, v8, v9
	v_cvt_pk_bf16_f32 v1, v10, v11
	v_cvt_pk_bf16_f32 v2, v12, v13
	v_cvt_pk_bf16_f32 v3, v14, v15
	v_mov_b64_e32 v[220:221], v[16:17]
	ds_bpermute_b32 v212, v216, v0
	ds_bpermute_b32 v213, v216, v1
	ds_bpermute_b32 v214, v216, v2
	ds_bpermute_b32 v215, v216, v3
	s_waitcnt lgkmcnt(4)
	global_store_dwordx4 v[218:219], v[208:211], off
	s_waitcnt lgkmcnt(0)
	global_store_dwordx4 v[220:221], v[212:215], off offset:256
	s_cbranch_vccnz .LBB0_68
